# LN1/LN2 wave_sum butterflies: 6 dependent ds_bpermute round trips replaced by DPP quad_perm/mirror adds + permlane16/32 swaps (bit-identical sums); on top of j2
# baseline (speedup 1.0000x reference)
; __device__ __forceinline__ float bf_lo(unsigned w) { return __uint_as_float(w << 16); }
; __device__ __forceinline__ float bf_hi(unsigned w) { return __uint_as_float(w & 0xffff0000u); }
; __device__ __forceinline__ const float* mod_ptr(unsigned char* ws, int l, int r) { const int v = r < T ? (r >> 13) : 4; return (const float*)(ws + WS_MOD) + (size_t)(l * 5 + v) * 6144; }
; __device__ __forceinline__ void ph_ln1_router(const Ctx& X, CArgs a, int l, int nrows) {
;     ...
;     for (int r0 = gw * 2; r0 < nrows; r0 += NGW * 2) {
;         const float* md = uni(mod_ptr(X.ws, l, r0));
;         unsigned l4 = 4u * (unsigned)X.lane; asm volatile("" : "+v"(l4));
;         float* x1p = uni(X1 + (size_t)r0 * D); unsigned char* h2p = uni(H2 + (size_t)r0 * D);
;         f32x4 v[2][4]; float s[2] = {0.f, 0.f};
; #pragma unroll
;         for (int j = 0; j < 4; ++j) { v[0][j] = xn[0][j]; v[1][j] = xn[1][j]; }
; #pragma unroll
;         for (int j = 0; j < 4; ++j) { const f32x4 g1 = *(const f32x4*)(md + (l4 + 2048u + 256u * j));
; #pragma unroll
;             for (int q = 0; q < 2; ++q) { const v2u ow = on[q][j]; const f32x4 of = {bf_lo(ow.x), bf_hi(ow.x), bf_lo(ow.y), bf_hi(ow.y)};
;                 v[q][j] = v[q][j] * DN_ALPHA + g1 * of;
;                 s[q] += (v[q][j][0] + v[q][j][1]) + (v[q][j][2] + v[q][j][3]); } }
;         float mean[2], rstd[2];
; #pragma unroll
;         for (int q = 0; q < 2; ++q) mean[q] = wave_sum(s[q]) * (1.0f / D);
.LBB0_1413:
	s_min_i32 s14, s24, 0x8000
	s_ashr_i32 s14, s14, 13
	s_add_i32 s14, s14, s44
	s_mul_hi_i32 s15, s14, 0x6000
	s_mulk_i32 s14, 0x6000
	s_add_u32 s26, s37, s14
	v_mov_b32_e32 v64, v108
	s_addc_u32 s27, s38, s15
	s_waitcnt vmcnt(7)
	v_lshlrev_b32_e32 v38, 16, v62
	v_add_u32_e32 v0, 0x800, v64
	s_waitcnt lgkmcnt(0)
	v_lshl_add_u64 v[34:35], v[0:1], 2, s[26:27]
	global_load_dwordx4 v[34:37], v[34:35], off
	v_and_b32_e32 v39, 0xffff0000, v62
	v_lshlrev_b32_e32 v40, 16, v63
	v_and_b32_e32 v41, 0xffff0000, v63
	s_mov_b32 s14, 0x3fb504f3
	s_waitcnt vmcnt(7)
	v_lshlrev_b32_e32 v42, 16, v59
	v_and_b32_e32 v43, 0xffff0000, v59
	s_waitcnt vmcnt(6)
	v_lshlrev_b32_e32 v44, 16, v61
	v_and_b32_e32 v45, 0xffff0000, v61
	s_waitcnt vmcnt(5)
	v_lshlrev_b32_e32 v68, 16, v57
	v_and_b32_e32 v69, 0xffff0000, v57
	s_waitcnt vmcnt(4)
	v_lshlrev_b32_e32 v70, 16, v55
	v_and_b32_e32 v71, 0xffff0000, v55
	s_waitcnt vmcnt(2)
	v_lshlrev_b32_e32 v94, 16, v52
	v_and_b32_e32 v95, 0xffff0000, v52
	v_lshlrev_b32_e32 v96, 16, v53
	v_and_b32_e32 v97, 0xffff0000, v53
	s_mov_b32 s25, 0xf800000
	v_mov_b32_e32 v65, v1
	v_lshlrev_b64 v[106:107], 2, v[64:65]
	s_waitcnt vmcnt(0)
	v_pk_mul_f32 v[40:41], v[36:37], v[40:41]
	v_pk_mul_f32 v[38:39], v[34:35], v[38:39]
	v_pk_fma_f32 v[86:87], v[4:5], s[14:15], v[40:41] op_sel_hi:[1,0,1]
	v_pk_fma_f32 v[88:89], v[2:3], s[14:15], v[38:39] op_sel_hi:[1,0,1]
	v_mov_b32_e32 v41, v87
	v_pk_mov_b32 v[38:39], v[88:89], v[86:87] op_sel:[1,0]
	v_mov_b32_e32 v40, v88
	v_pk_add_f32 v[38:39], v[38:39], v[40:41]
	v_pk_mul_f32 v[36:37], v[36:37], v[42:43]
	v_add_f32_e32 v0, v38, v39
	v_lshlrev_b32_e32 v38, 16, v58
	v_and_b32_e32 v39, 0xffff0000, v58
	v_pk_mul_f32 v[34:35], v[34:35], v[38:39]
	v_pk_fma_f32 v[66:67], v[8:9], s[14:15], v[36:37] op_sel_hi:[1,0,1]
	v_pk_fma_f32 v[72:73], v[6:7], s[14:15], v[34:35] op_sel_hi:[1,0,1]
	v_mov_b32_e32 v37, v67
	v_pk_mov_b32 v[34:35], v[72:73], v[66:67] op_sel:[1,0]
	v_mov_b32_e32 v36, v72
	v_pk_add_f32 v[34:35], v[34:35], v[36:37]
	v_add_f32_e32 v40, 0, v0
	v_add_f32_e32 v0, v34, v35
	v_add_f32_e32 v38, 0, v0
	v_add_u32_e32 v0, 0x900, v64
	v_lshl_add_u64 v[34:35], v[0:1], 2, s[26:27]
	global_load_dwordx4 v[34:37], v[34:35], off
	v_lshlrev_b32_e32 v42, 16, v60
	v_and_b32_e32 v43, 0xffff0000, v60
	v_add_u32_e32 v0, 0xa00, v64
	s_waitcnt vmcnt(0)
	v_pk_mul_f32 v[44:45], v[36:37], v[44:45]
	v_pk_mul_f32 v[42:43], v[34:35], v[42:43]
	v_pk_fma_f32 v[84:85], v[12:13], s[14:15], v[44:45] op_sel_hi:[1,0,1]
	v_pk_fma_f32 v[82:83], v[10:11], s[14:15], v[42:43] op_sel_hi:[1,0,1]
	v_mov_b32_e32 v45, v85
	v_pk_mov_b32 v[42:43], v[82:83], v[84:85] op_sel:[1,0]
	v_mov_b32_e32 v44, v82
	v_pk_add_f32 v[42:43], v[42:43], v[44:45]
	v_pk_mul_f32 v[36:37], v[36:37], v[68:69]
	v_pk_add_f32 v[44:45], v[42:43], v[42:43] op_sel:[0,1] op_sel_hi:[1,0]
	v_lshlrev_b32_e32 v42, 16, v56
	v_and_b32_e32 v43, 0xffff0000, v56
	v_pk_mul_f32 v[34:35], v[34:35], v[42:43]
	v_pk_fma_f32 v[76:77], v[16:17], s[14:15], v[36:37] op_sel_hi:[1,0,1]
	v_pk_fma_f32 v[74:75], v[14:15], s[14:15], v[34:35] op_sel_hi:[1,0,1]
	v_mov_b32_e32 v37, v77
	v_pk_mov_b32 v[34:35], v[74:75], v[76:77] op_sel:[1,0]
	v_mov_b32_e32 v36, v74
	v_pk_add_f32 v[34:35], v[34:35], v[36:37]
	v_lshlrev_b32_e32 v68, 16, v54
	v_pk_add_f32 v[42:43], v[34:35], v[34:35] op_sel:[0,1] op_sel_hi:[1,0]
	v_lshl_add_u64 v[34:35], v[0:1], 2, s[26:27]
	global_load_dwordx4 v[34:37], v[34:35], off
	v_and_b32_e32 v69, 0xffff0000, v54
	v_add_u32_e32 v0, 0xb00, v64
	s_waitcnt vmcnt(0)
	v_pk_mul_f32 v[68:69], v[34:35], v[68:69]
	v_pk_mul_f32 v[70:71], v[36:37], v[70:71]
	v_pk_fma_f32 v[78:79], v[18:19], s[14:15], v[68:69] op_sel_hi:[1,0,1]
	v_lshlrev_b32_e32 v68, 16, v50
	v_and_b32_e32 v69, 0xffff0000, v50
	v_pk_fma_f32 v[80:81], v[20:21], s[14:15], v[70:71] op_sel_hi:[1,0,1]
	v_lshlrev_b32_e32 v70, 16, v51
	v_and_b32_e32 v71, 0xffff0000, v51
	v_pk_mul_f32 v[34:35], v[34:35], v[68:69]
	v_pk_mul_f32 v[36:37], v[36:37], v[70:71]
	v_pk_fma_f32 v[68:69], v[22:23], s[14:15], v[34:35] op_sel_hi:[1,0,1]
	v_lshl_add_u64 v[34:35], v[0:1], 2, s[26:27]
	v_pk_fma_f32 v[70:71], v[24:25], s[14:15], v[36:37] op_sel_hi:[1,0,1]
	global_load_dwordx4 v[34:37], v[34:35], off
	v_add_f32_e32 v90, v78, v79
	v_add_f32_e32 v92, v80, v81
	v_add_f32_e32 v98, v68, v69
	v_add_f32_e32 v100, v70, v71
	s_waitcnt vmcnt(0)
	v_pk_mul_f32 v[96:97], v[36:37], v[96:97]
	v_pk_mul_f32 v[94:95], v[34:35], v[94:95]
	v_pk_fma_f32 v[96:97], v[28:29], s[14:15], v[96:97] op_sel_hi:[1,0,1]
	v_pk_fma_f32 v[94:95], v[26:27], s[14:15], v[94:95] op_sel_hi:[1,0,1]
	v_mov_b32_e32 v91, v96
	v_mov_b32_e32 v41, v94
	v_mov_b32_e32 v45, v95
	v_mov_b32_e32 v93, v97
	v_pk_add_f32 v[40:41], v[40:41], v[44:45]
	v_pk_add_f32 v[44:45], v[90:91], v[92:93]
	s_nop 0
	v_pk_add_f32 v[40:41], v[40:41], v[44:45]
	v_lshlrev_b32_e32 v44, 16, v49
	v_add_f32_e32 v0, v40, v41
	v_lshlrev_b32_e32 v40, 16, v48
	v_and_b32_e32 v41, 0xffff0000, v48
	v_and_b32_e32 v45, 0xffff0000, v49
	v_pk_mul_f32 v[36:37], v[36:37], v[44:45]
	v_pk_mul_f32 v[34:35], v[34:35], v[40:41]
	v_pk_fma_f32 v[90:91], v[32:33], s[14:15], v[36:37] op_sel_hi:[1,0,1]
	v_pk_fma_f32 v[92:93], v[30:31], s[14:15], v[34:35] op_sel_hi:[1,0,1]
	v_mov_b32_e32 v99, v90
	v_mov_b32_e32 v39, v92
	v_mov_b32_e32 v43, v93
	v_mov_b32_e32 v101, v91
	v_pk_add_f32 v[34:35], v[38:39], v[42:43]
	v_pk_add_f32 v[36:37], v[98:99], v[100:101]
	v_mov_b32_e32 v99, v1
	v_pk_add_f32 v[34:35], v[34:35], v[36:37]
	s_nop 0
	v_add_f32_e32 v34, v34, v35
	s_waitcnt lgkmcnt(0)
	s_nop 1
	v_add_f32_dpp v0, v0, v0 quad_perm:[1,0,3,2] row_mask:0xf bank_mask:0xf
	s_waitcnt lgkmcnt(0)
	s_nop 1
	v_add_f32_dpp v0, v0, v0 quad_perm:[2,3,0,1] row_mask:0xf bank_mask:0xf
	s_waitcnt lgkmcnt(0)
; __device__ __forceinline__ void ph_ln1_router(const Ctx& X, CArgs a, int l, int nrows) {
;     ...
;         for (int q = 0; q < 2; ++q) mean[q] = wave_sum(s[q]) * (1.0f / D);
; #pragma unroll
;         for (int q = 0; q < 2; ++q) { float qq = 0.f;
; #pragma unroll
;             for (int j = 0; j < 4; ++j) { v[q][j] = v[q][j] - mean[q]; qq += (v[q][j][0] * v[q][j][0] + v[q][j][1] * v[q][j][1]) + (v[q][j][2] * v[q][j][2] + v[q][j][3] * v[q][j][3]); }
;             s[q] = qq; }
; #pragma unroll
;         for (int q = 0; q < 2; ++q) rstd[q] = 1.0f / sqrtf(wave_sum(s[q]) * (1.0f / D) + LN_EPS);
	s_nop 1
	v_add_f32_dpp v0, v0, v0 row_half_mirror row_mask:0xf bank_mask:0xf
	s_waitcnt lgkmcnt(0)
	s_nop 1
	v_add_f32_dpp v0, v0, v0 row_mirror row_mask:0xf bank_mask:0xf
	v_mov_b32_e32 v35, v0
	s_waitcnt lgkmcnt(0)
	s_nop 1
	v_permlane16_swap_b32_e32 v0, v35
	v_add_f32_e32 v0, v0, v35
	v_mov_b32_e32 v35, v0
	s_waitcnt lgkmcnt(0)
	s_nop 1
	v_permlane32_swap_b32_e32 v0, v35
	v_add_f32_e32 v42, v0, v35
	v_fmamk_f32 v89, v42, 0xba800000, v89
	v_fmac_f32_e32 v88, 0xba800000, v42
	v_fmamk_f32 v87, v42, 0xba800000, v87
	v_fmac_f32_e32 v86, 0xba800000, v42
	s_waitcnt lgkmcnt(0)
	s_nop 1
	v_add_f32_dpp v0, v34, v34 quad_perm:[1,0,3,2] row_mask:0xf bank_mask:0xf
	v_pk_mul_f32 v[36:37], v[88:89], v[88:89]
	v_fmamk_f32 v83, v42, 0xba800000, v83
	v_fmac_f32_e32 v82, 0xba800000, v42
	v_fmamk_f32 v85, v42, 0xba800000, v85
	s_waitcnt lgkmcnt(0)
	s_nop 1
	v_add_f32_dpp v0, v0, v0 quad_perm:[2,3,0,1] row_mask:0xf bank_mask:0xf
	v_fmac_f32_e32 v84, 0xba800000, v42
	v_fmac_f32_e32 v78, 0xba800000, v42
	v_fmamk_f32 v79, v42, 0xba800000, v79
	v_fmac_f32_e32 v80, 0xba800000, v42
	s_waitcnt lgkmcnt(0)
	s_nop 1
	v_add_f32_dpp v0, v0, v0 row_half_mirror row_mask:0xf bank_mask:0xf
	v_fmamk_f32 v81, v42, 0xba800000, v81
	v_fmamk_f32 v97, v42, 0xba800000, v97
	v_fmac_f32_e32 v96, 0xba800000, v42
	v_fmamk_f32 v95, v42, 0xba800000, v95
	s_waitcnt lgkmcnt(0)
	s_nop 1
	v_add_f32_dpp v0, v0, v0 row_mirror row_mask:0xf bank_mask:0xf
	v_mov_b32_e32 v34, v0
	v_fmac_f32_e32 v94, 0xba800000, v42
	s_waitcnt lgkmcnt(0)
	s_nop 1
	v_permlane16_swap_b32_e32 v0, v34
	v_add_f32_e32 v0, v0, v34
	v_mov_b32_e32 v34, v0
	s_waitcnt lgkmcnt(0)
	s_nop 1
	v_permlane32_swap_b32_e32 v0, v34
	v_add_f32_e32 v43, v0, v34
	v_pk_mul_f32 v[34:35], v[86:87], v[86:87]
	v_mul_f32_e32 v0, v78, v78
	v_pk_mov_b32 v[38:39], v[36:37], v[34:35] op_sel:[1,0]
	v_mov_b32_e32 v37, v35
	v_pk_add_f32 v[34:35], v[38:39], v[36:37]
	v_pk_mul_f32 v[36:37], v[84:85], v[84:85]
	v_pk_mul_f32 v[38:39], v[82:83], v[82:83]
	v_pk_add_f32 v[34:35], v[34:35], v[34:35] op_sel_hi:[0,1]
	v_pk_mov_b32 v[40:41], v[38:39], v[36:37] op_sel:[1,0]
	v_mov_b32_e32 v39, v37
	v_pk_add_f32 v[36:37], v[40:41], v[38:39]
	v_pk_fma_f32 v[38:39], v[78:79], v[78:79], v[0:1] op_sel_hi:[1,1,0]
	v_mul_f32_e32 v0, v80, v80
	v_pk_add_f32 v[36:37], v[36:37], v[36:37] op_sel_hi:[0,1]
	v_pk_fma_f32 v[40:41], v[80:81], v[80:81], v[0:1] op_sel_hi:[1,1,0]
	v_mul_f32_e32 v38, v94, v94
	v_mul_f32_e32 v40, v95, v95
	v_mul_f32_e32 v34, v96, v96
	v_mul_f32_e32 v36, v97, v97
	v_pk_add_f32 v[38:39], v[38:39], v[40:41]
	v_pk_add_f32 v[34:35], v[34:35], v[36:37]
	v_fmamk_f32 v73, v43, 0xba800000, v73
	v_pk_add_f32 v[34:35], v[38:39], v[34:35]
	v_fmac_f32_e32 v72, 0xba800000, v43
	v_fmamk_f32 v67, v43, 0xba800000, v67
	v_fmac_f32_e32 v66, 0xba800000, v43
	v_add_f32_e32 v42, v34, v35
	v_pk_mul_f32 v[34:35], v[66:67], v[66:67]
	v_pk_mul_f32 v[36:37], v[72:73], v[72:73]
	v_fmamk_f32 v75, v43, 0xba800000, v75
	v_pk_mov_b32 v[38:39], v[36:37], v[34:35] op_sel:[1,0]
	v_mov_b32_e32 v37, v35
	v_fmac_f32_e32 v74, 0xba800000, v43
	v_fmamk_f32 v77, v43, 0xba800000, v77
	v_fmac_f32_e32 v76, 0xba800000, v43
	v_pk_add_f32 v[34:35], v[38:39], v[36:37]
	v_pk_mul_f32 v[36:37], v[76:77], v[76:77]
	v_pk_mul_f32 v[38:39], v[74:75], v[74:75]
	v_fmac_f32_e32 v68, 0xba800000, v43
	v_pk_mov_b32 v[40:41], v[38:39], v[36:37] op_sel:[1,0]
	v_mov_b32_e32 v39, v37
	v_fmamk_f32 v69, v43, 0xba800000, v69
	v_fmac_f32_e32 v70, 0xba800000, v43
	v_mul_f32_e32 v0, v68, v68
	v_pk_add_f32 v[36:37], v[40:41], v[38:39]
	v_fmamk_f32 v71, v43, 0xba800000, v71
	v_pk_fma_f32 v[38:39], v[68:69], v[68:69], v[0:1] op_sel_hi:[1,1,0]
	v_mul_f32_e32 v0, v70, v70
	v_pk_add_f32 v[34:35], v[34:35], v[34:35] op_sel_hi:[0,1]
	v_pk_add_f32 v[36:37], v[36:37], v[36:37] op_sel_hi:[0,1]
	v_pk_fma_f32 v[40:41], v[70:71], v[70:71], v[0:1] op_sel_hi:[1,1,0]
	v_fmamk_f32 v91, v43, 0xba800000, v91
	v_fmac_f32_e32 v90, 0xba800000, v43
	v_fmamk_f32 v93, v43, 0xba800000, v93
	v_fmac_f32_e32 v92, 0xba800000, v43
	v_mul_f32_e32 v38, v92, v92
	v_mul_f32_e32 v40, v93, v93
	v_mul_f32_e32 v34, v90, v90
	v_mul_f32_e32 v36, v91, v91
	v_pk_add_f32 v[38:39], v[38:39], v[40:41]
	v_pk_add_f32 v[34:35], v[34:35], v[36:37]
	s_nop 0
	v_pk_add_f32 v[34:35], v[38:39], v[34:35]
	s_nop 0
	v_add_f32_e32 v0, v34, v35
	s_waitcnt lgkmcnt(0)
	s_nop 1
	v_add_f32_dpp v34, v42, v42 quad_perm:[1,0,3,2] row_mask:0xf bank_mask:0xf
	s_waitcnt lgkmcnt(0)
	s_nop 1
	v_add_f32_dpp v34, v34, v34 quad_perm:[2,3,0,1] row_mask:0xf bank_mask:0xf
	s_waitcnt lgkmcnt(0)
	s_nop 1
	v_add_f32_dpp v34, v34, v34 row_half_mirror row_mask:0xf bank_mask:0xf
	s_waitcnt lgkmcnt(0)
	s_nop 1
	v_add_f32_dpp v34, v34, v34 row_mirror row_mask:0xf bank_mask:0xf
	v_mov_b32_e32 v35, v34
	s_waitcnt lgkmcnt(0)
	s_nop 1
	v_permlane16_swap_b32_e32 v34, v35
	v_add_f32_e32 v34, v34, v35
	v_mov_b32_e32 v35, v34
	s_waitcnt lgkmcnt(0)
	s_nop 1
	v_permlane32_swap_b32_e32 v34, v35
	v_add_f32_e32 v34, v34, v35
	v_fmamk_f32 v34, v34, 0x3a800000, v239
	v_cmp_gt_f32_e32 vcc, s25, v34
	v_mul_f32_e32 v35, 0x4f800000, v34
	s_nop 0
	v_cndmask_b32_e32 v34, v34, v35, vcc
	v_sqrt_f32_e32 v35, v34
	s_nop 0
	v_add_u32_e32 v36, -1, v35
	v_fma_f32 v37, -v36, v35, v34
	v_cmp_ge_f32_e64 s[14:15], 0, v37
	v_add_u32_e32 v37, 1, v35
	s_nop 0
	v_cndmask_b32_e64 v36, v35, v36, s[14:15]
	v_fma_f32 v35, -v37, v35, v34
	v_cmp_lt_f32_e64 s[14:15], 0, v35
	s_nop 1
	v_cndmask_b32_e64 v35, v36, v37, s[14:15]
	v_mul_f32_e32 v36, 0x37800000, v35
	v_cndmask_b32_e32 v35, v35, v36, vcc
	v_cmp_class_f32_e32 vcc, v34, v238
	s_nop 1
	v_cndmask_b32_e32 v34, v35, v34, vcc
	v_div_scale_f32 v35, s[14:15], v34, v34, 1.0
	v_rcp_f32_e32 v36, v35
	s_nop 0
	v_fma_f32 v37, -v35, v36, 1.0
	v_fmac_f32_e32 v36, v37, v36
	v_div_scale_f32 v37, vcc, 1.0, v34, 1.0
	v_mul_f32_e32 v38, v37, v36
	v_fma_f32 v39, -v35, v38, v37
	v_fmac_f32_e32 v38, v39, v36
	v_fma_f32 v35, -v35, v38, v37
	v_div_fmas_f32 v35, v35, v36, v38
	v_div_fixup_f32 v100, v35, v34, 1.0
	v_pk_mul_f32 v[88:89], v[88:89], v[100:101] op_sel_hi:[1,0]
	v_pk_mul_f32 v[86:87], v[86:87], v[100:101] op_sel_hi:[1,0]
	s_waitcnt lgkmcnt(0)
; __device__ __forceinline__ unsigned pk_fp8x4(float a, float b, float c, float d) { int w = 0; w = __builtin_amdgcn_cvt_pk_fp8_f32(clamp448(a), clamp448(b), w, false); w = __builtin_amdgcn_cvt_pk_fp8_f32(clamp448(c), clamp448(d), w, true); return (unsigned)w; }
; __device__ __forceinline__ void ph_ln1_router(const Ctx& X, CArgs a, int l, int nrows) {
;     ...
;         for (int q = 0; q < 2; ++q) rstd[q] = 1.0f / sqrtf(wave_sum(s[q]) * (1.0f / D) + LN_EPS);
; #pragma unroll
;         for (int j = 0; j < 4; ++j) { const unsigned c = l4 + 256u * j;
;             const f32x4 g4 = *(const f32x4*)(lg + c), b4 = *(const f32x4*)(lb + c), sc4 = *(const f32x4*)(md + (c + 4096u)) + 1.0f, sh4 = *(const f32x4*)(md + (c + 3072u));
; #pragma unroll
;             for (int q = 0; q < 2; ++q) { const f32x4 y = v[q][j] * rstd[q] * g4 + b4;
;                 *(f32x4*)(x1p + (c + 1024u * q)) = y;
;                 const f32x4 h = y * sc4 + sh4; v[q][j] = h;
;                 *(unsigned*)(h2p + (c + 1024u * q)) = pg8::pk_fp8x4(h[0], h[1], h[2], h[3]); } }
	s_nop 1
	v_add_f32_dpp v0, v0, v0 quad_perm:[1,0,3,2] row_mask:0xf bank_mask:0xf
	s_waitcnt lgkmcnt(0)
	s_nop 1
	v_add_f32_dpp v0, v0, v0 quad_perm:[2,3,0,1] row_mask:0xf bank_mask:0xf
	s_waitcnt lgkmcnt(0)
	s_nop 1
	v_add_f32_dpp v0, v0, v0 row_half_mirror row_mask:0xf bank_mask:0xf
	s_waitcnt lgkmcnt(0)
	s_nop 1
	v_add_f32_dpp v0, v0, v0 row_mirror row_mask:0xf bank_mask:0xf
	v_mov_b32_e32 v34, v0
	s_waitcnt lgkmcnt(0)
	s_nop 1
	v_permlane16_swap_b32_e32 v0, v34
	v_add_f32_e32 v0, v0, v34
	v_mov_b32_e32 v34, v0
	s_waitcnt lgkmcnt(0)
	s_nop 1
	v_permlane32_swap_b32_e32 v0, v34
	v_add_f32_e32 v0, v0, v34
	v_fmamk_f32 v0, v0, 0x3a800000, v239
	v_cmp_gt_f32_e32 vcc, s25, v0
	v_mul_f32_e32 v34, 0x4f800000, v0
	s_nop 0
	v_cndmask_b32_e32 v0, v0, v34, vcc
	v_sqrt_f32_e32 v34, v0
	s_nop 0
	v_add_u32_e32 v35, -1, v34
	v_fma_f32 v36, -v35, v34, v0
	v_cmp_ge_f32_e64 s[14:15], 0, v36
	v_add_u32_e32 v36, 1, v34
	s_nop 0
	v_cndmask_b32_e64 v35, v34, v35, s[14:15]
	v_fma_f32 v34, -v36, v34, v0
	v_cmp_lt_f32_e64 s[14:15], 0, v34
	s_nop 1
	v_cndmask_b32_e64 v34, v35, v36, s[14:15]
	v_mul_f32_e32 v35, 0x37800000, v34
	v_cndmask_b32_e32 v34, v34, v35, vcc
	v_cmp_class_f32_e32 vcc, v0, v238
	s_nop 1
	v_cndmask_b32_e32 v0, v34, v0, vcc
	v_div_scale_f32 v34, s[14:15], v0, v0, 1.0
	v_rcp_f32_e32 v35, v34
	s_nop 0
	v_fma_f32 v36, -v34, v35, 1.0
	v_fmac_f32_e32 v35, v36, v35
	v_div_scale_f32 v36, vcc, 1.0, v0, 1.0
	v_mul_f32_e32 v37, v36, v35
	v_fma_f32 v38, -v34, v37, v36
	v_fmac_f32_e32 v37, v38, v35
	v_fma_f32 v34, -v34, v37, v36
	v_div_fmas_f32 v34, v34, v35, v37
	v_div_fixup_f32 v98, v34, v0, 1.0
	v_add_u32_e32 v0, 0x1000, v64
	v_lshl_add_u64 v[42:43], v[0:1], 2, s[26:27]
	global_load_dwordx4 v[42:45], v[42:43], off
	v_lshl_add_u64 v[34:35], s[18:19], 0, v[106:107]
	v_lshl_add_u64 v[38:39], s[20:21], 0, v[106:107]
	v_add_u32_e32 v0, 0xc00, v64
	global_load_dwordx4 v[34:37], v[34:35], off
	s_waitcnt vmcnt(1)
	v_pk_add_f32 v[102:103], v[42:43], 1.0 op_sel_hi:[1,0]
	global_load_dwordx4 v[38:41], v[38:39], off
	v_lshl_add_u64 v[42:43], v[0:1], 2, s[26:27]
	v_pk_add_f32 v[104:105], v[44:45], 1.0 op_sel_hi:[1,0]
	global_load_dwordx4 v[42:45], v[42:43], off
	s_waitcnt vmcnt(1)
	v_pk_fma_f32 v[110:111], v[34:35], v[88:89], v[38:39]
	v_pk_fma_f32 v[112:113], v[36:37], v[86:87], v[40:41]
	v_lshl_add_u64 v[86:87], s[2:3], 0, v[106:107]
	s_waitcnt vmcnt(0)
	v_pk_fma_f32 v[88:89], v[102:103], v[110:111], v[42:43]
	global_store_dwordx4 v[86:87], v[110:113], off
	v_med3_f32 v0, v88, s59, v250
	v_med3_f32 v65, v89, s59, v250
	v_cvt_pk_fp8_f32 v99, v0, v65
	v_pk_fma_f32 v[86:87], v[104:105], v[112:113], v[44:45]
	s_nop 0
	v_med3_f32 v0, v86, s59, v250
	v_med3_f32 v65, v87, s59, v250
	v_cvt_pk_fp8_f32 v99, v0, v65 op_sel:[0,0,1]
	v_add_u32_e32 v0, 0x400, v64
	v_pk_mul_f32 v[72:73], v[72:73], v[98:99] op_sel_hi:[1,0]
	v_pk_mul_f32 v[66:67], v[66:67], v[98:99] op_sel_hi:[1,0]
	v_pk_fma_f32 v[34:35], v[34:35], v[72:73], v[38:39]
	v_pk_fma_f32 v[36:37], v[36:37], v[66:67], v[40:41]
	v_lshl_add_u64 v[38:39], v[0:1], 2, s[2:3]
	v_pk_fma_f32 v[72:73], v[102:103], v[34:35], v[42:43]
	global_store_dword v64, v99, s[22:23]
	global_store_dwordx4 v[38:39], v[34:37], off
	v_pk_fma_f32 v[66:67], v[104:105], v[36:37], v[44:45]
	v_add_u32_e32 v42, 0x1100, v64
	v_med3_f32 v34, v72, s59, v250
	v_med3_f32 v35, v73, s59, v250
	v_mov_b32_e32 v36, v1
	v_cvt_pk_fp8_f32 v36, v34, v35
	v_med3_f32 v34, v66, s59, v250
	v_med3_f32 v35, v67, s59, v250
	v_mov_b32_e32 v43, v1
	v_cvt_pk_fp8_f32 v36, v34, v35 op_sel:[0,0,1]
	v_lshl_add_u64 v[42:43], v[42:43], 2, s[26:27]
	v_pk_mul_f32 v[68:69], v[68:69], v[98:99] op_sel_hi:[1,0]
	v_pk_mul_f32 v[70:71], v[70:71], v[98:99] op_sel_hi:[1,0]
	global_store_dword v0, v36, s[22:23]
	global_load_dwordx4 v[42:45], v[42:43], off
	v_add_u32_e32 v0, 0x100, v64
	v_lshlrev_b64 v[106:107], 2, v[0:1]
	v_lshl_add_u64 v[34:35], s[18:19], 0, v[106:107]
	v_lshl_add_u64 v[38:39], s[20:21], 0, v[106:107]
	global_load_dwordx4 v[34:37], v[34:35], off
	v_pk_mul_f32 v[92:93], v[92:93], v[98:99] op_sel_hi:[1,0]
	global_load_dwordx4 v[38:41], v[38:39], off
	v_pk_mul_f32 v[90:91], v[90:91], v[98:99] op_sel_hi:[1,0]
	s_waitcnt vmcnt(2)
	v_pk_add_f32 v[112:113], v[42:43], 1.0 op_sel_hi:[1,0]
	v_add_u32_e32 v42, 0xd00, v64
	v_mov_b32_e32 v43, v1
	v_lshl_add_u64 v[42:43], v[42:43], 2, s[26:27]
	global_load_dwordx4 v[102:105], v[42:43], off
	v_pk_mul_f32 v[42:43], v[82:83], v[100:101] op_sel_hi:[1,0]
	v_pk_add_f32 v[110:111], v[44:45], 1.0 op_sel_hi:[1,0]
	v_pk_mul_f32 v[44:45], v[84:85], v[100:101] op_sel_hi:[1,0]
	s_waitcnt vmcnt(1)
	v_pk_fma_f32 v[42:43], v[42:43], v[34:35], v[38:39]
	v_pk_fma_f32 v[44:45], v[44:45], v[36:37], v[40:41]
	v_lshl_add_u64 v[82:83], s[2:3], 0, v[106:107]
	global_store_dwordx4 v[82:83], v[42:45], off
	s_waitcnt vmcnt(1)
; __device__ __forceinline__ unsigned pk_fp8x4(float a, float b, float c, float d) { int w = 0; w = __builtin_amdgcn_cvt_pk_fp8_f32(clamp448(a), clamp448(b), w, false); w = __builtin_amdgcn_cvt_pk_fp8_f32(clamp448(c), clamp448(d), w, true); return (unsigned)w; }
; __device__ __forceinline__ void ph_ln1_router(const Ctx& X, CArgs a, int l, int nrows) {
;     ...
;         for (int j = 0; j < 4; ++j) { const unsigned c = l4 + 256u * j;
;             const f32x4 g4 = *(const f32x4*)(lg + c), b4 = *(const f32x4*)(lb + c), sc4 = *(const f32x4*)(md + (c + 4096u)) + 1.0f, sh4 = *(const f32x4*)(md + (c + 3072u));
; #pragma unroll
;             for (int q = 0; q < 2; ++q) { const f32x4 y = v[q][j] * rstd[q] * g4 + b4;
;                 *(f32x4*)(x1p + (c + 1024u * q)) = y;
;                 const f32x4 h = y * sc4 + sh4; v[q][j] = h;
;                 *(unsigned*)(h2p + (c + 1024u * q)) = pg8::pk_fp8x4(h[0], h[1], h[2], h[3]); } }
;         __builtin_amdgcn_sched_barrier(0);
;         if (r0 + NGW * 2 < nrows) LN1_FETCH(r0 + NGW * 2);
	v_pk_fma_f32 v[84:85], v[42:43], v[112:113], v[102:103]
	v_pk_fma_f32 v[82:83], v[44:45], v[110:111], v[104:105]
	v_med3_f32 v42, v84, s59, v250
	v_med3_f32 v43, v85, s59, v250
	v_mov_b32_e32 v44, v1
	v_cvt_pk_fp8_f32 v44, v42, v43
	v_med3_f32 v42, v82, s59, v250
	v_med3_f32 v43, v83, s59, v250
	v_cvt_pk_fp8_f32 v44, v42, v43 op_sel:[0,0,1]
	v_pk_mul_f32 v[42:43], v[76:77], v[98:99] op_sel_hi:[1,0]
	global_store_dword v0, v44, s[22:23]
	v_pk_mul_f32 v[44:45], v[74:75], v[98:99] op_sel_hi:[1,0]
	v_add_u32_e32 v0, 0x500, v64
	v_pk_fma_f32 v[34:35], v[34:35], v[44:45], v[38:39]
	v_pk_fma_f32 v[36:37], v[36:37], v[42:43], v[40:41]
	v_lshl_add_u64 v[38:39], v[0:1], 2, s[2:3]
	v_pk_fma_f32 v[44:45], v[112:113], v[34:35], v[102:103]
	global_store_dwordx4 v[38:39], v[34:37], off
	v_pk_fma_f32 v[42:43], v[110:111], v[36:37], v[104:105]
	v_add_u32_e32 v74, 0x1200, v64
	v_med3_f32 v34, v44, s59, v250
	v_med3_f32 v35, v45, s59, v250
	v_mov_b32_e32 v36, v1
	v_cvt_pk_fp8_f32 v36, v34, v35
	v_med3_f32 v34, v42, s59, v250
	v_med3_f32 v35, v43, s59, v250
	v_mov_b32_e32 v75, v1
	v_cvt_pk_fp8_f32 v36, v34, v35 op_sel:[0,0,1]
	v_lshl_add_u64 v[74:75], v[74:75], 2, s[26:27]
	global_store_dword v0, v36, s[22:23]
	global_load_dwordx4 v[74:77], v[74:75], off
	v_add_u32_e32 v0, 0x200, v64
	v_lshlrev_b64 v[106:107], 2, v[0:1]
	v_lshl_add_u64 v[34:35], s[18:19], 0, v[106:107]
	v_lshl_add_u64 v[38:39], s[20:21], 0, v[106:107]
	global_load_dwordx4 v[34:37], v[34:35], off
	s_waitcnt vmcnt(1)
	v_pk_add_f32 v[112:113], v[74:75], 1.0 op_sel_hi:[1,0]
	v_add_u32_e32 v74, 0xe00, v64
	v_mov_b32_e32 v75, v1
	global_load_dwordx4 v[38:41], v[38:39], off
	v_lshl_add_u64 v[74:75], v[74:75], 2, s[26:27]
	global_load_dwordx4 v[102:105], v[74:75], off
	v_pk_add_f32 v[110:111], v[76:77], 1.0 op_sel_hi:[1,0]
	v_pk_mul_f32 v[74:75], v[80:81], v[100:101] op_sel_hi:[1,0]
	v_pk_mul_f32 v[76:77], v[78:79], v[100:101] op_sel_hi:[1,0]
	s_waitcnt vmcnt(1)
	v_pk_fma_f32 v[78:79], v[74:75], v[36:37], v[40:41]
	v_pk_fma_f32 v[76:77], v[76:77], v[34:35], v[38:39]
	v_lshl_add_u64 v[74:75], s[2:3], 0, v[106:107]
	global_store_dwordx4 v[74:75], v[76:79], off
	s_waitcnt vmcnt(1)
	v_pk_fma_f32 v[74:75], v[78:79], v[110:111], v[104:105]
	v_pk_fma_f32 v[34:35], v[68:69], v[34:35], v[38:39]
	v_pk_fma_f32 v[76:77], v[76:77], v[112:113], v[102:103]
	v_mov_b32_e32 v79, v1
	v_med3_f32 v65, v76, s59, v250
	v_med3_f32 v78, v77, s59, v250
	v_cvt_pk_fp8_f32 v79, v65, v78
	v_med3_f32 v65, v74, s59, v250
	v_med3_f32 v78, v75, s59, v250
	v_pk_fma_f32 v[36:37], v[70:71], v[36:37], v[40:41]
	v_cvt_pk_fp8_f32 v79, v65, v78 op_sel:[0,0,1]
	v_pk_fma_f32 v[40:41], v[34:35], v[112:113], v[102:103]
	global_store_dword v0, v79, s[22:23]
	v_add_u32_e32 v0, 0x600, v64
	v_lshl_add_u64 v[38:39], v[0:1], 2, s[2:3]
	global_store_dwordx4 v[38:39], v[34:37], off
	v_pk_fma_f32 v[38:39], v[36:37], v[110:111], v[104:105]
	s_nop 0
	v_med3_f32 v34, v40, s59, v250
	v_med3_f32 v35, v41, s59, v250
	v_mov_b32_e32 v36, v1
	v_cvt_pk_fp8_f32 v36, v34, v35
	v_med3_f32 v34, v38, s59, v250
	v_med3_f32 v35, v39, s59, v250
	v_cvt_pk_fp8_f32 v36, v34, v35 op_sel:[0,0,1]
	global_store_dword v0, v36, s[22:23]
	v_add_u32_e32 v0, 0x300, v64
	v_lshlrev_b64 v[106:107], 2, v[0:1]
	v_lshl_add_u64 v[68:69], s[20:21], 0, v[106:107]
	global_load_dwordx4 v[78:81], v[68:69], off
	v_add_u32_e32 v68, 0x1300, v64
	v_mov_b32_e32 v69, v1
	v_lshl_add_u64 v[68:69], v[68:69], 2, s[26:27]
	global_load_dwordx4 v[68:71], v[68:69], off
	v_lshl_add_u64 v[34:35], s[18:19], 0, v[106:107]
	global_load_dwordx4 v[34:37], v[34:35], off
	s_waitcnt vmcnt(1)
	v_pk_add_f32 v[112:113], v[68:69], 1.0 op_sel_hi:[1,0]
	v_add_u32_e32 v68, 0xf00, v64
	v_mov_b32_e32 v69, v1
	v_lshl_add_u64 v[68:69], v[68:69], 2, s[26:27]
	global_load_dwordx4 v[102:105], v[68:69], off
	v_pk_add_f32 v[110:111], v[70:71], 1.0 op_sel_hi:[1,0]
	v_pk_mul_f32 v[70:71], v[94:95], v[100:101] op_sel_hi:[1,0]
	v_pk_mul_f32 v[68:69], v[96:97], v[100:101] op_sel_hi:[1,0]
	s_waitcnt vmcnt(1)
	v_pk_fma_f32 v[94:95], v[70:71], v[34:35], v[78:79]
	v_pk_fma_f32 v[96:97], v[68:69], v[36:37], v[80:81]
	v_lshl_add_u64 v[68:69], s[2:3], 0, v[106:107]
	global_store_dwordx4 v[68:69], v[94:97], off
	v_pk_fma_f32 v[78:79], v[92:93], v[34:35], v[78:79]
	v_pk_fma_f32 v[80:81], v[90:91], v[36:37], v[80:81]
	s_waitcnt vmcnt(1)
	v_pk_fma_f32 v[70:71], v[94:95], v[112:113], v[102:103]
	s_nop 0
	v_med3_f32 v65, v70, s59, v250
	v_med3_f32 v94, v71, s59, v250
	v_mov_b32_e32 v95, v1
	v_cvt_pk_fp8_f32 v95, v65, v94
	v_pk_fma_f32 v[68:69], v[96:97], v[110:111], v[104:105]
	v_pk_fma_f32 v[36:37], v[78:79], v[112:113], v[102:103]
	v_med3_f32 v65, v68, s59, v250
	v_med3_f32 v94, v69, s59, v250
	v_cvt_pk_fp8_f32 v95, v65, v94 op_sel:[0,0,1]
	v_med3_f32 v65, v36, s59, v250
	global_store_dword v0, v95, s[22:23]
	v_add_u32_e32 v0, 0x700, v64
	v_lshl_add_u64 v[34:35], v[0:1], 2, s[2:3]
	global_store_dwordx4 v[34:35], v[78:81], off
	v_pk_fma_f32 v[34:35], v[80:81], v[110:111], v[104:105]
	s_nop 0
	v_med3_f32 v78, v37, s59, v250
	v_mov_b32_e32 v79, v1
	v_cvt_pk_fp8_f32 v79, v65, v78
	v_med3_f32 v65, v34, s59, v250
	v_med3_f32 v78, v35, s59, v250
	v_cvt_pk_fp8_f32 v79, v65, v78 op_sel:[0,0,1]
	global_store_dword v0, v79, s[22:23]
	v_readlane_b32 s14, v254, 49
	s_add_i32 s24, s24, s14
	v_readlane_b32 s15, v254, 50
	s_cmp_ge_i32 s24, s41
	s_cselect_b64 s[14:15], -1, 0
	s_and_b64 vcc, exec, s[14:15]
	s_cbranch_vccnz .LBB0_1429
	v_readlane_b32 s26, v254, 57
	v_readlane_b32 s27, v254, 58
	v_mov_b32_e32 v0, v108
	s_mov_b64 s[28:29], -1
	s_and_b64 vcc, exec, s[26:27]
	s_cbranch_vccz .LBB0_1416
	s_ashr_i32 s25, s24, 31
	s_lshl_b64 s[26:27], s[24:25], 12
	s_add_u32 s26, s39, s26
	s_addc_u32 s27, s40, s27
	s_mov_b64 s[28:29], 0

; __device__ __forceinline__ void ph_ln2(const Ctx& X, CArgs a, int l, int nrows) {
;     ...
;     for (int r0 = gw * 2; r0 < nrows; r0 += NGW * 2) {
;         const float* md = mod_ptr(X.ws, l, r0);
;         const bool isc = r0 >= T; const int b = isc ? (r0 - T) >> 8 : r0 >> 13;
;         const int slv = slv_n; const float afv = afv_n;
;         f32x4 v[2][4], mo[2][4];
; #pragma unroll
;         for (int q = 0; q < 2; ++q)
; #pragma unroll
;             for (int j = 0; j < 4; ++j) { v[q][j] = xn[q][j]; mo[q][j] = (f32x4){0.f, 0.f, 0.f, 0.f}; }
;         const unsigned long long bal = __ballot(slv >= 0);
;         unsigned msk[2] = {(unsigned)(bal & 0xffffull), (unsigned)((bal >> 16) & 0xffffull)};
;         const size_t rb = (size_t)(isc ? 4096 + b * CAPC : b * CAP);
;         while ((msk[0] | msk[1]) != 0u) {
;             v2u wv[2][4][4]; float af[2][4];
; #pragma unroll
;             for (int q = 0; q < 2; ++q) { unsigned m = msk[q];
; #pragma unroll
;                 for (int k = 0; k < 4; ++k) { const bool has = m != 0u; const int e = has ? __builtin_ctz(m) : 0; m = has ? (m & (m - 1u)) : 0u;
;                     int sl = 0; float aq = 0.f;
;                     if (has) { sl = __builtin_amdgcn_readlane(slv, q * 16 + e); aq = __builtin_bit_cast(float, __builtin_amdgcn_readlane(__builtin_bit_cast(int, afv), q * 16 + e)); }
;                     af[q][k] = aq; const size_t er = (size_t)e * EROWS + rb + sl;
; #pragma unroll
;                     for (int j = 0; j < 4; ++j) wv[q][k][j] = *(const v2u*)(EO + er * D + 4 * X.lane + 256 * j); }
;                 msk[q] = m; }
; #pragma unroll
;             for (int q = 0; q < 2; ++q)
; #pragma unroll
;                 for (int k = 0; k < 4; ++k)
; #pragma unroll
;                     for (int j = 0; j < 4; ++j) { const v2u w2 = wv[q][k][j]; const float aq = af[q][k];
;                         mo[q][j][0] += aq * bf_lo(w2.x); mo[q][j][1] += aq * bf_hi(w2.x); mo[q][j][2] += aq * bf_lo(w2.y); mo[q][j][3] += aq * bf_hi(w2.y); }
;         }
;         __builtin_amdgcn_sched_barrier(0);
;         if (r0 + NGW * 2 < nrows) LN2_FETCH(r0 + NGW * 2);
;         __builtin_amdgcn_sched_barrier(0);
;         float s[2] = {0.f, 0.f}, mean[2], rstd[2];
; #pragma unroll
;         for (int q = 0; q < 2; ++q)
; #pragma unroll
;             for (int j = 0; j < 4; ++j) { const int c = 4 * X.lane + 256 * j;
.LBB0_2347:
	s_min_i32 s6, s8, 0x8000
	s_ashr_i32 s6, s6, 13
	s_add_i32 s6, s6, s37
	s_mul_hi_i32 s7, s6, 0x6000
	s_mulk_i32 s6, 0x6000
	s_add_u32 s6, s2, s6
	s_addc_u32 s7, s3, s7
	v_lshlrev_b32_e32 v0, 2, v66
	v_lshl_add_u64 v[140:141], s[6:7], 0, v[0:1]
	s_mov_b64 s[6:7], 0x15000
	v_lshl_add_u64 v[148:149], v[140:141], 0, s[6:7]
	s_mov_b32 s6, 0x15000
	v_add_co_u32_e32 v140, vcc, s6, v140
	s_mov_b32 s6, 0x3fb504f3
	s_nop 0
	v_addc_co_u32_e32 v141, vcc, 0, v141, vcc
	global_load_dwordx4 v[140:143], v[140:141], off
	v_readlane_b32 s22, v254, 57
	global_load_dwordx4 v[144:147], v[148:149], off offset:2048
	v_readlane_b32 s23, v254, 58
	s_mov_b64 s[18:19], -1
	s_waitcnt vmcnt(1)
	v_pk_mul_f32 v[116:117], v[116:117], v[142:143]
	v_pk_mul_f32 v[118:119], v[118:119], v[140:141]
	v_pk_fma_f32 v[116:117], v[64:65], s[6:7], v[116:117] op_sel_hi:[1,0,1]
	v_pk_fma_f32 v[118:119], v[62:63], s[6:7], v[118:119] op_sel_hi:[1,0,1]
	v_mov_b32_e32 v65, v117
	v_pk_mov_b32 v[62:63], v[118:119], v[116:117] op_sel:[1,0]
	v_mov_b32_e32 v64, v118
	v_pk_add_f32 v[62:63], v[62:63], v[64:65]
	v_pk_mul_f32 v[122:123], v[122:123], v[142:143]
	v_add_f32_e32 v62, v62, v63
	v_add_f32_e32 v150, 0, v62
	global_load_dwordx4 v[62:65], v[148:149], off offset:1024
	s_waitcnt vmcnt(0)
	v_pk_mul_f32 v[108:109], v[108:109], v[64:65]
	v_pk_mul_f32 v[110:111], v[110:111], v[62:63]
	v_pk_fma_f32 v[108:109], v[60:61], s[6:7], v[108:109] op_sel_hi:[1,0,1]
	v_pk_fma_f32 v[110:111], v[58:59], s[6:7], v[110:111] op_sel_hi:[1,0,1]
	v_mov_b32_e32 v61, v109
	v_pk_mov_b32 v[58:59], v[110:111], v[108:109] op_sel:[1,0]
	v_mov_b32_e32 v60, v110
	v_pk_add_f32 v[58:59], v[58:59], v[60:61]
	v_pk_mul_f32 v[60:61], v[138:139], v[144:145]
	v_pk_add_f32 v[152:153], v[58:59], v[58:59] op_sel:[0,1] op_sel_hi:[1,0]
	v_pk_mul_f32 v[58:59], v[136:137], v[146:147]
	v_pk_fma_f32 v[60:61], v[54:55], s[6:7], v[60:61] op_sel_hi:[1,0,1]
	v_pk_fma_f32 v[58:59], v[56:57], s[6:7], v[58:59] op_sel_hi:[1,0,1]
	global_load_dwordx4 v[54:57], v[148:149], off offset:3072
	v_add_f32_e32 v136, v60, v61
	v_add_f32_e32 v138, v58, v59
	s_waitcnt vmcnt(0)
	v_pk_mul_f32 v[132:133], v[132:133], v[56:57]
	v_pk_mul_f32 v[134:135], v[134:135], v[54:55]
	v_pk_fma_f32 v[52:53], v[52:53], s[6:7], v[132:133] op_sel_hi:[1,0,1]
	v_pk_fma_f32 v[50:51], v[50:51], s[6:7], v[134:135] op_sel_hi:[1,0,1]
	v_mov_b32_e32 v137, v52
	v_mov_b32_e32 v151, v50
	v_mov_b32_e32 v153, v51
	v_mov_b32_e32 v139, v53
	v_pk_add_f32 v[132:133], v[150:151], v[152:153]
	v_pk_add_f32 v[134:135], v[136:137], v[138:139]
	s_nop 0
	v_pk_add_f32 v[132:133], v[132:133], v[134:135]
	s_nop 0
	v_add_f32_e32 v67, v132, v133
	v_pk_mul_f32 v[132:133], v[120:121], v[140:141]
	v_pk_fma_f32 v[120:121], v[48:49], s[6:7], v[122:123] op_sel_hi:[1,0,1]
	v_pk_fma_f32 v[122:123], v[46:47], s[6:7], v[132:133] op_sel_hi:[1,0,1]
	v_mov_b32_e32 v49, v121
	v_pk_mov_b32 v[46:47], v[122:123], v[120:121] op_sel:[1,0]
	v_mov_b32_e32 v48, v122
	v_pk_add_f32 v[46:47], v[46:47], v[48:49]
	v_pk_mul_f32 v[48:49], v[112:113], v[62:63]
	v_add_f32_e32 v46, v46, v47
	v_add_f32_e32 v132, 0, v46
	v_pk_mul_f32 v[46:47], v[114:115], v[64:65]
	v_pk_fma_f32 v[114:115], v[42:43], s[6:7], v[48:49] op_sel_hi:[1,0,1]
	v_pk_fma_f32 v[112:113], v[44:45], s[6:7], v[46:47] op_sel_hi:[1,0,1]
	v_mov_b32_e32 v44, v114
	v_pk_mov_b32 v[42:43], v[114:115], v[112:113] op_sel:[1,0]
	v_mov_b32_e32 v45, v113
	v_pk_add_f32 v[42:43], v[42:43], v[44:45]
	v_pk_mul_f32 v[44:45], v[130:131], v[146:147]
	v_pk_mul_f32 v[46:47], v[128:129], v[144:145]
	v_pk_fma_f32 v[62:63], v[40:41], s[6:7], v[44:45] op_sel_hi:[1,0,1]
	v_pk_mul_f32 v[44:45], v[126:127], v[56:57]
	v_pk_mul_f32 v[48:49], v[124:125], v[54:55]
	v_pk_add_f32 v[42:43], v[42:43], v[42:43] op_sel:[0,1] op_sel_hi:[1,0]
	v_pk_fma_f32 v[64:65], v[38:39], s[6:7], v[46:47] op_sel_hi:[1,0,1]
	v_pk_fma_f32 v[46:47], v[36:37], s[6:7], v[44:45] op_sel_hi:[1,0,1]
	v_pk_fma_f32 v[48:49], v[34:35], s[6:7], v[48:49] op_sel_hi:[1,0,1]
	v_add_f32_e32 v38, v64, v65
	v_add_f32_e32 v40, v62, v63
	v_mov_b32_e32 v133, v48
	v_mov_b32_e32 v43, v49
	v_mov_b32_e32 v39, v46
	v_mov_b32_e32 v41, v47
	v_pk_add_f32 v[34:35], v[132:133], v[42:43]
	v_pk_add_f32 v[36:37], v[38:39], v[40:41]
	s_mov_b32 s6, 0xf800000
	v_pk_add_f32 v[34:35], v[34:35], v[36:37]
	s_nop 0
	v_add_f32_e32 v34, v34, v35
	s_waitcnt lgkmcnt(0)
	s_nop 1
	v_add_f32_dpp v35, v67, v67 quad_perm:[1,0,3,2] row_mask:0xf bank_mask:0xf
	s_waitcnt lgkmcnt(0)
	s_nop 1
	v_add_f32_dpp v35, v35, v35 quad_perm:[2,3,0,1] row_mask:0xf bank_mask:0xf
	s_waitcnt lgkmcnt(0)
	s_nop 1
	v_add_f32_dpp v35, v35, v35 row_half_mirror row_mask:0xf bank_mask:0xf
	s_waitcnt lgkmcnt(0)
	s_nop 1
	v_add_f32_dpp v35, v35, v35 row_mirror row_mask:0xf bank_mask:0xf
	v_mov_b32_e32 v36, v35
	s_waitcnt lgkmcnt(0)
	s_nop 1
	v_permlane16_swap_b32_e32 v35, v36
	v_add_f32_e32 v35, v35, v36
	v_mov_b32_e32 v36, v35
	s_waitcnt lgkmcnt(0)
	s_nop 1
	v_permlane32_swap_b32_e32 v35, v36
	v_add_f32_e32 v42, v35, v36
	v_fmamk_f32 v119, v42, 0xba800000, v119
	v_fmac_f32_e32 v118, 0xba800000, v42
	v_fmamk_f32 v117, v42, 0xba800000, v117
	v_fmac_f32_e32 v116, 0xba800000, v42
	s_waitcnt lgkmcnt(0)
	s_nop 1
	v_add_f32_dpp v34, v34, v34 quad_perm:[1,0,3,2] row_mask:0xf bank_mask:0xf
	v_pk_mul_f32 v[36:37], v[118:119], v[118:119]
	v_fmamk_f32 v109, v42, 0xba800000, v109
	v_fmac_f32_e32 v108, 0xba800000, v42
	v_fmamk_f32 v111, v42, 0xba800000, v111
	s_waitcnt lgkmcnt(0)
	s_nop 1
	v_add_f32_dpp v34, v34, v34 quad_perm:[2,3,0,1] row_mask:0xf bank_mask:0xf
	v_fmac_f32_e32 v110, 0xba800000, v42
	v_fmac_f32_e32 v60, 0xba800000, v42
	v_fmac_f32_e32 v58, 0xba800000, v42
	v_fmamk_f32 v61, v42, 0xba800000, v61
	s_waitcnt lgkmcnt(0)
; #define GAS __attribute__((address_space(1)))
; __device__ __forceinline__ unsigned cvt_pk_bf16(float lo, float hi) { const f32x2_cv v = {lo, hi}; const bf16x2_cv b = __builtin_convertvector(v, bf16x2_cv); return __builtin_bit_cast(unsigned, b); }
; __device__ __forceinline__ void ph_ln2(const Ctx& X, CArgs a, int l, int nrows) {
;     ...
;         if (r0 + NGW * 2 < nrows) LN2_FETCH(r0 + NGW * 2);
;         __builtin_amdgcn_sched_barrier(0);
;         float s[2] = {0.f, 0.f}, mean[2], rstd[2];
; #pragma unroll
;         for (int q = 0; q < 2; ++q)
; #pragma unroll
;             for (int j = 0; j < 4; ++j) { const int c = 4 * X.lane + 256 * j;
;                 v[q][j] = v[q][j] * DN_ALPHA + *(const f32x4*)(md + 5120 + c) * mo[q][j];
;                 s[q] += (v[q][j][0] + v[q][j][1]) + (v[q][j][2] + v[q][j][3]); }
; #pragma unroll
;         for (int q = 0; q < 2; ++q) mean[q] = wave_sum(s[q]) * (1.0f / D);
; #pragma unroll
;         for (int q = 0; q < 2; ++q) { float qq = 0.f;
; #pragma unroll
;             for (int j = 0; j < 4; ++j) { v[q][j] = v[q][j] - mean[q]; qq += (v[q][j][0] * v[q][j][0] + v[q][j][1] * v[q][j][1]) + (v[q][j][2] * v[q][j][2] + v[q][j][3] * v[q][j][3]); }
;             s[q] = qq; }
; #pragma unroll
;         for (int q = 0; q < 2; ++q) rstd[q] = 1.0f / sqrtf(wave_sum(s[q]) * (1.0f / D) + LN_EPS);
;         const float* md1 = (const float*)(X.ws + WS_MOD) + (size_t)(1 * 5 + (isc ? 4 : b)) * 6144;
; #pragma unroll
;         for (int j = 0; j < 4; ++j) { const int c = 4 * X.lane + 256 * j; const f32x4 g4 = *(const f32x4*)(lg + c), b4 = *(const f32x4*)(lb + c);
; #pragma unroll
;             for (int q = 0; q < 2; ++q) { const f32x4 y = v[q][j] * rstd[q] * g4 + b4;
;                 if (l == 0) { *(f32x4*)(X2 + (size_t)(r0 + q) * D + c) = y;
;                     const f32x4 h = y * (*(const f32x4*)(md1 + 1024 + c) + 1.0f) + *(const f32x4*)(md1 + c);
;                     v2u wv; wv.x = cvt_pk_bf16(h[0], h[1]); wv.y = cvt_pk_bf16(h[2], h[3]); *(v2u*)(XH + (size_t)(r0 + q) * D + c) = wv;
;                     *(unsigned*)(X.ws + WS_XH8 + (size_t)(r0 + q) * D + c) = pg8::pk_fp8x4(h[0], h[1], h[2], h[3]); }
;                 else *(f32x4*)((float*)(GAS float*)a->out + (size_t)(r0 + q) * D + c) = y; } }
	s_nop 1
	v_add_f32_dpp v34, v34, v34 row_half_mirror row_mask:0xf bank_mask:0xf
	v_fmamk_f32 v59, v42, 0xba800000, v59
	v_fmamk_f32 v53, v42, 0xba800000, v53
	v_fmac_f32_e32 v52, 0xba800000, v42
	v_fmamk_f32 v51, v42, 0xba800000, v51
	s_waitcnt lgkmcnt(0)
	s_nop 1
	v_add_f32_dpp v34, v34, v34 row_mirror row_mask:0xf bank_mask:0xf
	v_mov_b32_e32 v35, v34
	v_fmac_f32_e32 v50, 0xba800000, v42
	s_waitcnt lgkmcnt(0)
	s_nop 1
	v_permlane16_swap_b32_e32 v34, v35
	v_add_f32_e32 v34, v34, v35
	v_mov_b32_e32 v35, v34
	s_waitcnt lgkmcnt(0)
	s_nop 1
	v_permlane32_swap_b32_e32 v34, v35
	v_add_f32_e32 v43, v34, v35
	v_pk_mul_f32 v[34:35], v[116:117], v[116:117]
	v_fmamk_f32 v121, v43, 0xba800000, v121
	v_pk_mov_b32 v[38:39], v[36:37], v[34:35] op_sel:[1,0]
	v_mov_b32_e32 v37, v35
	v_pk_add_f32 v[34:35], v[38:39], v[36:37]
	v_pk_mul_f32 v[36:37], v[108:109], v[108:109]
	v_pk_add_f32 v[34:35], v[34:35], v[34:35] op_sel_hi:[0,1]
	v_pk_mul_f32 v[38:39], v[110:111], v[110:111]
	v_mul_f32_e32 v34, v60, v60
	v_pk_mov_b32 v[40:41], v[38:39], v[36:37] op_sel:[1,0]
	v_mov_b32_e32 v39, v37
	v_pk_add_f32 v[36:37], v[40:41], v[38:39]
	v_pk_fma_f32 v[38:39], v[60:61], v[60:61], v[34:35] op_sel_hi:[1,1,0]
	v_mul_f32_e32 v34, v58, v58
	v_pk_add_f32 v[36:37], v[36:37], v[36:37] op_sel_hi:[0,1]
	v_pk_fma_f32 v[40:41], v[58:59], v[58:59], v[34:35] op_sel_hi:[1,1,0]
	v_mul_f32_e32 v38, v50, v50
	v_mul_f32_e32 v40, v51, v51
	v_mul_f32_e32 v34, v52, v52
	v_mul_f32_e32 v36, v53, v53
	v_pk_add_f32 v[38:39], v[38:39], v[40:41]
	v_pk_add_f32 v[34:35], v[34:35], v[36:37]
	v_fmamk_f32 v123, v43, 0xba800000, v123
	v_pk_add_f32 v[34:35], v[38:39], v[34:35]
	v_fmac_f32_e32 v120, 0xba800000, v43
	v_add_f32_e32 v34, v34, v35
	v_fmac_f32_e32 v122, 0xba800000, v43
	v_mul_f32_e32 v35, v123, v123
	v_mul_f32_e32 v36, v121, v121
	v_fmac_f32_e32 v35, v122, v122
	v_fmac_f32_e32 v36, v120, v120
	v_fmamk_f32 v113, v43, 0xba800000, v113
	v_fmamk_f32 v115, v43, 0xba800000, v115
	v_add_f32_e32 v35, v35, v36
	v_fmac_f32_e32 v112, 0xba800000, v43
	v_fmac_f32_e32 v114, 0xba800000, v43
	v_mul_f32_e32 v36, v115, v115
	v_mul_f32_e32 v37, v113, v113
	v_fmac_f32_e32 v36, v114, v114
	v_fmac_f32_e32 v37, v112, v112
	v_add_f32_e32 v36, v36, v37
	v_fmamk_f32 v63, v43, 0xba800000, v63
	v_fmamk_f32 v65, v43, 0xba800000, v65
	v_add_f32_e32 v35, v35, v36
	v_fmac_f32_e32 v62, 0xba800000, v43
	v_fmac_f32_e32 v64, 0xba800000, v43
	v_mul_f32_e32 v36, v65, v65
	v_mul_f32_e32 v37, v63, v63
	v_fmac_f32_e32 v36, v64, v64
	v_fmac_f32_e32 v37, v62, v62
	v_add_f32_e32 v36, v36, v37
	v_fmamk_f32 v47, v43, 0xba800000, v47
	v_fmamk_f32 v49, v43, 0xba800000, v49
	v_add_f32_e32 v35, v36, v35
	v_fmac_f32_e32 v46, 0xba800000, v43
	v_fmac_f32_e32 v48, 0xba800000, v43
	v_mul_f32_e32 v36, v49, v49
	v_mul_f32_e32 v37, v47, v47
	v_fmac_f32_e32 v36, v48, v48
	v_fmac_f32_e32 v37, v46, v46
	v_add_f32_e32 v36, v36, v37
	v_add_f32_e32 v35, v36, v35
	s_waitcnt lgkmcnt(0)
	s_nop 1
	v_add_f32_dpp v34, v34, v34 quad_perm:[1,0,3,2] row_mask:0xf bank_mask:0xf
	s_waitcnt lgkmcnt(0)
	s_nop 1
	v_add_f32_dpp v34, v34, v34 quad_perm:[2,3,0,1] row_mask:0xf bank_mask:0xf
	s_waitcnt lgkmcnt(0)
	s_nop 1
	v_add_f32_dpp v34, v34, v34 row_half_mirror row_mask:0xf bank_mask:0xf
	s_waitcnt lgkmcnt(0)
	s_nop 1
	v_add_f32_dpp v34, v34, v34 row_mirror row_mask:0xf bank_mask:0xf
	v_mov_b32_e32 v36, v34
	s_waitcnt lgkmcnt(0)
	s_nop 1
	v_permlane16_swap_b32_e32 v34, v36
	v_add_f32_e32 v34, v34, v36
	v_mov_b32_e32 v36, v34
	s_waitcnt lgkmcnt(0)
	s_nop 1
	v_permlane32_swap_b32_e32 v34, v36
	v_add_f32_e32 v34, v34, v36
	v_fmamk_f32 v34, v34, 0x3a800000, v239
	v_cmp_gt_f32_e32 vcc, s6, v34
	v_mul_f32_e32 v36, 0x4f800000, v34
	s_nop 0
	v_cndmask_b32_e32 v34, v34, v36, vcc
	v_sqrt_f32_e32 v36, v34
	s_nop 0
	v_add_u32_e32 v37, -1, v36
	v_fma_f32 v38, -v37, v36, v34
	v_cmp_ge_f32_e64 s[6:7], 0, v38
	v_add_u32_e32 v38, 1, v36
	s_nop 0
	v_cndmask_b32_e64 v37, v36, v37, s[6:7]
	v_fma_f32 v36, -v38, v36, v34
	v_cmp_lt_f32_e64 s[6:7], 0, v36
	s_nop 1
	v_cndmask_b32_e64 v36, v37, v38, s[6:7]
	v_mul_f32_e32 v37, 0x37800000, v36
	v_cndmask_b32_e32 v36, v36, v37, vcc
	v_cmp_class_f32_e32 vcc, v34, v238
	s_nop 1
	v_cndmask_b32_e32 v34, v36, v34, vcc
	v_div_scale_f32 v36, s[6:7], v34, v34, 1.0
	v_rcp_f32_e32 v37, v36
	s_lshl_b64 s[6:7], s[16:17], 2
	s_add_u32 s6, s31, s6
	s_addc_u32 s7, s33, s7
	v_fma_f32 v38, -v36, v37, 1.0
	v_fmac_f32_e32 v37, v38, v37
	v_div_scale_f32 v38, vcc, 1.0, v34, 1.0
	v_mul_f32_e32 v39, v38, v37
	v_fma_f32 v40, -v36, v39, v38
	v_fmac_f32_e32 v39, v40, v37
	v_fma_f32 v36, -v36, v39, v38
	v_div_fmas_f32 v36, v36, v37, v39
	v_div_fixup_f32 v54, v36, v34, 1.0
	s_add_u32 s16, s6, 0x1000
	s_addc_u32 s17, s7, 0
	v_lshl_add_u64 v[206:207], s[16:17], 0, v[0:1]
	v_lshl_add_u64 v[208:209], s[6:7], 0, v[0:1]
	global_load_dwordx4 v[130:133], v[74:75], off
	global_load_dwordx4 v[154:157], v[76:77], off
	global_load_dwordx4 v[134:137], v[74:75], off offset:1024
	global_load_dwordx4 v[158:161], v[76:77], off offset:1024
	global_load_dwordx4 v[138:141], v[74:75], off offset:2048
	global_load_dwordx4 v[162:165], v[76:77], off offset:2048
	global_load_dwordx4 v[142:145], v[74:75], off offset:3072
	global_load_dwordx4 v[166:169], v[76:77], off offset:3072
	global_load_dwordx4 v[174:177], v[206:207], off
	global_load_dwordx4 v[190:193], v[208:209], off
	global_load_dwordx4 v[178:181], v[206:207], off offset:1024
	global_load_dwordx4 v[194:197], v[208:209], off offset:1024
	global_load_dwordx4 v[182:185], v[206:207], off offset:2048
	global_load_dwordx4 v[198:201], v[208:209], off offset:2048
	global_load_dwordx4 v[186:189], v[206:207], off offset:3072
	global_load_dwordx4 v[202:205], v[208:209], off offset:3072
	s_and_b64 vcc, exec, s[22:23]
	s_waitcnt lgkmcnt(0)
	s_nop 1
	v_add_f32_dpp v34, v35, v35 quad_perm:[1,0,3,2] row_mask:0xf bank_mask:0xf
	s_waitcnt lgkmcnt(0)
	s_nop 1
	v_add_f32_dpp v34, v34, v34 quad_perm:[2,3,0,1] row_mask:0xf bank_mask:0xf
	s_waitcnt lgkmcnt(0)
	s_nop 1
	v_add_f32_dpp v34, v34, v34 row_half_mirror row_mask:0xf bank_mask:0xf
	s_waitcnt lgkmcnt(0)
	s_nop 1
	v_add_f32_dpp v34, v34, v34 row_mirror row_mask:0xf bank_mask:0xf
	v_mov_b32_e32 v35, v34
	s_waitcnt lgkmcnt(0)
	s_nop 1
	v_permlane16_swap_b32_e32 v34, v35
	v_add_f32_e32 v55, v34, v35
	s_waitcnt vmcnt(0)
	s_nop 1
	v_mov_b64_e32 v[34:35], v[130:131]
	v_mov_b64_e32 v[36:37], v[132:133]
	s_nop 1
	v_mov_b64_e32 v[38:39], v[154:155]
	v_mov_b64_e32 v[40:41], v[156:157]
	v_mov_b32_e32 v67, v55
	v_pk_mul_f32 v[42:43], v[118:119], v[54:55] op_sel_hi:[1,0]
	v_pk_mul_f32 v[44:45], v[116:117], v[54:55] op_sel_hi:[1,0]
	v_pk_fma_f32 v[42:43], v[34:35], v[42:43], v[38:39]
	v_pk_fma_f32 v[44:45], v[36:37], v[44:45], v[40:41]
	s_cbranch_vccz .LBB0_2349
	s_load_dwordx2 s[18:19], s[12:13], 0xe0
	s_ashr_i32 s9, s8, 31
	s_lshl_b64 s[22:23], s[8:9], 12
	s_waitcnt lgkmcnt(0)
	s_add_u32 s18, s18, s22
	s_addc_u32 s19, s19, s23
	global_store_dwordx4 v0, v[42:45], s[18:19]
	s_mov_b64 s[18:19], 0

; #define GAS __attribute__((address_space(1)))
; __device__ __forceinline__ unsigned cvt_pk_bf16(float lo, float hi) { const f32x2_cv v = {lo, hi}; const bf16x2_cv b = __builtin_convertvector(v, bf16x2_cv); return __builtin_bit_cast(unsigned, b); }
; __device__ __forceinline__ unsigned pk_fp8x4(float a, float b, float c, float d) { int w = 0; w = __builtin_amdgcn_cvt_pk_fp8_f32(clamp448(a), clamp448(b), w, false); w = __builtin_amdgcn_cvt_pk_fp8_f32(clamp448(c), clamp448(d), w, true); return (unsigned)w; }
; __device__ __forceinline__ void ph_ln2(const Ctx& X, CArgs a, int l, int nrows) {
;     ...
;         for (int q = 0; q < 2; ++q) rstd[q] = 1.0f / sqrtf(wave_sum(s[q]) * (1.0f / D) + LN_EPS);
;         const float* md1 = (const float*)(X.ws + WS_MOD) + (size_t)(1 * 5 + (isc ? 4 : b)) * 6144;
; #pragma unroll
;         for (int j = 0; j < 4; ++j) { const int c = 4 * X.lane + 256 * j; const f32x4 g4 = *(const f32x4*)(lg + c), b4 = *(const f32x4*)(lb + c);
; #pragma unroll
;             for (int q = 0; q < 2; ++q) { const f32x4 y = v[q][j] * rstd[q] * g4 + b4;
;                 if (l == 0) { *(f32x4*)(X2 + (size_t)(r0 + q) * D + c) = y;
;                     const f32x4 h = y * (*(const f32x4*)(md1 + 1024 + c) + 1.0f) + *(const f32x4*)(md1 + c);
;                     v2u wv; wv.x = cvt_pk_bf16(h[0], h[1]); wv.y = cvt_pk_bf16(h[2], h[3]); *(v2u*)(XH + (size_t)(r0 + q) * D + c) = wv;
;                     *(unsigned*)(X.ws + WS_XH8 + (size_t)(r0 + q) * D + c) = pg8::pk_fp8x4(h[0], h[1], h[2], h[3]); }
;                 else *(f32x4*)((float*)(GAS float*)a->out + (size_t)(r0 + q) * D + c) = y; } }
.LBB0_2351:
	s_waitcnt lgkmcnt(0)
	s_nop 1
	v_permlane32_swap_b32_e32 v55, v67
	v_add_f32_e32 v42, v55, v67
	v_fmamk_f32 v42, v42, 0x3a800000, v239
	s_mov_b32 s6, 0xf800000
	v_mul_f32_e32 v43, 0x4f800000, v42
	v_cmp_gt_f32_e32 vcc, s6, v42
	v_readlane_b32 s18, v254, 57
	v_readlane_b32 s19, v254, 58
	v_cndmask_b32_e32 v42, v42, v43, vcc
	v_sqrt_f32_e32 v43, v42
	s_nop 0
	v_add_u32_e32 v44, -1, v43
	v_fma_f32 v55, -v44, v43, v42
	v_add_u32_e32 v45, 1, v43
	v_cmp_ge_f32_e64 s[6:7], 0, v55
	s_nop 1
	v_cndmask_b32_e64 v44, v43, v44, s[6:7]
	v_fma_f32 v43, -v45, v43, v42
	v_cmp_lt_f32_e64 s[6:7], 0, v43
	s_nop 1
	v_cndmask_b32_e64 v43, v44, v45, s[6:7]
	v_mul_f32_e32 v44, 0x37800000, v43
	v_cndmask_b32_e32 v43, v43, v44, vcc
	v_cmp_class_f32_e32 vcc, v42, v238
	s_nop 1
	v_cndmask_b32_e32 v42, v43, v42, vcc
	v_div_scale_f32 v43, s[6:7], v42, v42, 1.0
	v_rcp_f32_e32 v44, v43
	s_nop 0
	v_fma_f32 v45, -v43, v44, 1.0
	v_fmac_f32_e32 v44, v45, v44
	v_div_scale_f32 v45, vcc, 1.0, v42, 1.0
	v_mul_f32_e32 v55, v45, v44
	v_fma_f32 v67, -v43, v55, v45
	v_fmac_f32_e32 v55, v67, v44
	v_fma_f32 v43, -v43, v55, v45
	v_div_fmas_f32 v43, v43, v44, v55
	v_div_fixup_f32 v116, v43, v42, 1.0
	v_pk_mul_f32 v[42:43], v[122:123], v[116:117] op_sel_hi:[1,0]
	v_pk_mul_f32 v[44:45], v[120:121], v[116:117] op_sel_hi:[1,0]
	v_pk_fma_f32 v[34:35], v[34:35], v[42:43], v[38:39]
	v_cndmask_b32_e64 v38, 0, 1, s[18:19]
	v_pk_fma_f32 v[36:37], v[36:37], v[44:45], v[40:41]
	v_cmp_ne_u32_e64 s[6:7], 1, v38
	s_andn2_b64 vcc, exec, s[18:19]
	s_mov_b64 s[18:19], -1
	s_cbranch_vccnz .LBB0_2353
	s_load_dwordx2 s[18:19], s[12:13], 0xe0
	s_or_b32 s22, s8, 1
	s_ashr_i32 s23, s22, 31
	s_lshl_b64 s[22:23], s[22:23], 12
	s_waitcnt lgkmcnt(0)
	s_add_u32 s18, s18, s22
	s_addc_u32 s19, s19, s23
	global_store_dwordx4 v0, v[34:37], s[18:19]
	s_mov_b64 s[18:19], 0
